# SEL loop halves: 13 of 16 K-fragment LDS reads issued up front and 7 of 8 first V-fragment reads hoisted above the softmax
# speedup vs baseline: 1.0094x; 1.0094x over previous
.LBB0_1632:
	s_waitcnt vmcnt(0) lgkmcnt(0)
	s_barrier
	s_min_u32 s0, s95, 0xff
	s_lshl_b32 s0, s0, 2
	s_add_i32 s18, s0, 0x10200
	s_cmp_gt_u32 s95, s86
	s_cselect_b64 s[78:79], -1, 0
	s_and_b64 s[0:1], s[78:79], exec
	s_cselect_b32 s0, s94, s95
	s_lshl_b32 s56, s0, 14
	v_readfirstlane_b32 s24, v122
	s_add_i32 m0, s24, 0x8000
	v_lshl_add_u64 v[140:141], v[124:125], 0, s[56:57]
	global_load_lds_dwordx4 v[140:141], off
	s_add_u32 m0, m0, 0x1000
	v_lshl_add_u64 v[140:141], v[126:127], 0, s[56:57]
	global_load_lds_dwordx4 v[140:141], off
	s_add_u32 m0, m0, 0x1000
	v_lshl_add_u64 v[140:141], v[128:129], 0, s[56:57]
	global_load_lds_dwordx4 v[140:141], off
	s_add_u32 m0, m0, 0x1000
	v_lshl_add_u64 v[140:141], v[130:131], 0, s[56:57]
	global_load_lds_dwordx4 v[140:141], off
	s_add_u32 m0, m0, 0x1000
	v_lshl_add_u64 v[140:141], v[132:133], 0, s[56:57]
	global_load_lds_dwordx4 v[140:141], off
	s_add_u32 m0, m0, 0x1000
	v_lshl_add_u64 v[140:141], v[134:135], 0, s[56:57]
	global_load_lds_dwordx4 v[140:141], off
	s_add_u32 m0, m0, 0x1000
	v_lshl_add_u64 v[140:141], v[136:137], 0, s[56:57]
	global_load_lds_dwordx4 v[140:141], off
	s_add_u32 m0, m0, 0x1000
	v_lshl_add_u64 v[140:141], v[138:139], 0, s[56:57]
	global_load_lds_dwordx4 v[140:141], off
	v_mov_b32_e32 v0, s18
	ds_read_b32 v19, v0
	v_readfirstlane_b32 s0, v2
	s_nop 1
	v_ashrrev_i32_e64 v207, v185, s0
	v_and_b32_e32 v0, 15, v207
	v_cmp_ne_u32_e32 vcc, 0, v0
	s_and_saveexec_b64 s[80:81], vcc
	s_cbranch_execz .LBB0_1642
	v_and_b32_e32 v242, v207, v186
	v_cmp_ne_u32_e64 s[82:83], 0, v242
	ds_read_b128 v[0:3], v187
	ds_read_b128 v[4:7], v188
	ds_read_b128 v[8:11], v189
	ds_read_b128 v[12:15], v190
	ds_read_b128 v[148:151], v191
	ds_read_b128 v[152:155], v192
	ds_read_b128 v[156:159], v193
	ds_read_b128 v[208:211], v194
	ds_read_b128 v[226:229], v187 offset:8192
	ds_read_b128 v[230:233], v195
	ds_read_b128 v[234:237], v189 offset:8192
	ds_read_b128 v[238:241], v196
	ds_read_b128 v[212:215], v198
	s_waitcnt lgkmcnt(12)
	v_mfma_f32_16x16x32_bf16 v[0:3], v[0:3], v[20:23], 0
	s_waitcnt lgkmcnt(11)
	v_mfma_f32_16x16x32_bf16 v[4:7], v[4:7], v[20:23], 0
	s_waitcnt lgkmcnt(10)
	v_mfma_f32_16x16x32_bf16 v[0:3], v[8:11], v[24:27], v[0:3]
	s_waitcnt lgkmcnt(9)
	v_mfma_f32_16x16x32_bf16 v[4:7], v[12:15], v[24:27], v[4:7]
	s_waitcnt lgkmcnt(8)
	v_mfma_f32_16x16x32_bf16 v[0:3], v[148:151], v[28:31], v[0:3]
	ds_read_b128 v[148:151], v191 offset:8192
	s_waitcnt lgkmcnt(8)
	v_mfma_f32_16x16x32_bf16 v[4:7], v[152:155], v[28:31], v[4:7]
	ds_read_b128 v[152:155], v197
	s_waitcnt lgkmcnt(8)
	v_mfma_f32_16x16x32_bf16 v[160:163], v[156:159], v[32:35], v[0:3]
	s_waitcnt lgkmcnt(7)
	v_mfma_f32_16x16x32_bf16 v[156:159], v[208:211], v[32:35], v[4:7]
	ds_read_b128 v[208:211], v193 offset:8192
	s_waitcnt lgkmcnt(7)
	v_mfma_f32_16x16x32_bf16 v[0:3], v[226:229], v[20:23], 0
	s_waitcnt lgkmcnt(6)
	v_mfma_f32_16x16x32_bf16 v[4:7], v[230:233], v[20:23], 0
	s_waitcnt lgkmcnt(5)
	v_mfma_f32_16x16x32_bf16 v[0:3], v[234:237], v[24:27], v[0:3]
	s_waitcnt lgkmcnt(4)
	v_mfma_f32_16x16x32_bf16 v[4:7], v[238:241], v[24:27], v[4:7]
	s_waitcnt lgkmcnt(2)
	v_mfma_f32_16x16x32_bf16 v[0:3], v[148:151], v[28:31], v[0:3]
	s_waitcnt lgkmcnt(1)
	v_mfma_f32_16x16x32_bf16 v[4:7], v[152:155], v[28:31], v[4:7]
	s_waitcnt lgkmcnt(0)
	v_mfma_f32_16x16x32_bf16 v[152:155], v[208:211], v[32:35], v[0:3]
	v_mfma_f32_16x16x32_bf16 v[148:151], v[212:215], v[32:35], v[4:7]
	v_add_u32_e32 v242, v202, v203
	ds_read_b128 v[226:229], v242 offset:20480
	ds_read_b128 v[230:233], v242 offset:22528
	ds_read_b128 v[234:237], v242 offset:24576
	ds_read_b128 v[210:213], v242 offset:26624
	ds_read_b128 v[214:217], v242 offset:28672
	ds_read_b128 v[222:225], v242 offset:30720
	ds_read_b128 v[238:241], v242 offset:16384
	s_lshl_b32 s33, s94, 6
	s_or_b32 s0, s33, 63
	v_cmp_le_i32_e32 vcc, s0, v199
	s_and_saveexec_b64 s[0:1], vcc
	s_xor_b64 s[0:1], exec, s[0:1]
	s_or_saveexec_b64 s[26:27], s[0:1]
	s_mov_b64 s[84:85], s[82:83]
	s_xor_b64 exec, exec, s[26:27]
	s_cbranch_execz .LBB0_1635
	v_cndmask_b32_e64 v1, 0, -1, s[82:83]
	v_or_b32_e32 v2, s33, v201
	v_cndmask_b32_e64 v0, -1, v200, s[82:83]
	v_cmp_gt_i32_e64 s[0:1], v2, v1
	v_or_b32_e32 v1, 2, v2
	v_cmp_le_i32_e64 s[20:21], v1, v0
	v_or_b32_e32 v1, 3, v2
	v_cmp_le_i32_e64 s[22:23], v1, v0
	v_or_b32_e32 v1, 4, v2
	v_cmp_le_i32_e64 s[24:25], v1, v0
	v_or_b32_e32 v1, 5, v2
	v_cmp_le_i32_e64 s[28:29], v1, v0
	v_or_b32_e32 v1, 6, v2
	v_cmp_le_i32_e64 s[30:31], v1, v0
	v_or_b32_e32 v1, 7, v2
	v_cmp_le_i32_e64 s[34:35], v1, v0
	v_or_b32_e32 v1, 32, v2
	v_cmp_le_i32_e64 s[36:37], v1, v0
	v_cmp_lt_i32_e64 s[38:39], v1, v0
	v_or_b32_e32 v1, 34, v2
	v_cmp_le_i32_e64 s[40:41], v1, v0
	v_or_b32_e32 v1, 35, v2
	v_cmp_le_i32_e64 s[42:43], v1, v0
	v_or_b32_e32 v1, 36, v2
	v_cmp_le_i32_e64 s[44:45], v1, v0
	v_or_b32_e32 v1, 37, v2
	v_cmp_le_i32_e64 s[46:47], v1, v0
	v_or_b32_e32 v1, 38, v2
	v_cmp_le_i32_e64 s[18:19], v2, v0
	v_cmp_le_i32_e64 s[48:49], v1, v0
	v_or_b32_e32 v1, 39, v2
	s_and_b64 s[0:1], s[0:1], s[18:19]
	v_cmp_lt_i32_e64 s[18:19], v2, v0
	v_cmp_le_i32_e64 s[50:51], v1, v0
	v_cndmask_b32_e64 v160, v169, v160, s[0:1]
	v_cndmask_b32_e64 v161, v169, v161, s[18:19]
	v_cndmask_b32_e64 v162, v169, v162, s[20:21]
	v_cndmask_b32_e64 v163, v169, v163, s[22:23]
	v_cndmask_b32_e64 v156, v169, v156, s[24:25]
	v_cndmask_b32_e64 v157, v169, v157, s[28:29]
	v_cndmask_b32_e64 v158, v169, v158, s[30:31]
	v_cndmask_b32_e64 v159, v169, v159, s[34:35]
	v_cndmask_b32_e64 v152, v169, v152, s[36:37]
	v_cndmask_b32_e64 v153, v169, v153, s[38:39]
	v_cndmask_b32_e64 v154, v169, v154, s[40:41]
	v_cndmask_b32_e64 v155, v169, v155, s[42:43]
	v_cndmask_b32_e64 v148, v169, v148, s[44:45]
	v_cndmask_b32_e64 v149, v169, v149, s[46:47]
	v_cndmask_b32_e64 v150, v169, v150, s[48:49]
	v_cndmask_b32_e64 v151, v169, v151, s[50:51]
	s_andn2_b64 s[54:55], s[82:83], exec
	s_and_b64 s[50:51], s[50:51], exec
	s_and_b64 s[48:49], s[48:49], exec
	s_and_b64 s[46:47], s[46:47], exec
	s_and_b64 s[44:45], s[44:45], exec
	s_and_b64 s[42:43], s[42:43], exec
	s_and_b64 s[40:41], s[40:41], exec
	s_and_b64 s[38:39], s[38:39], exec
	s_and_b64 s[36:37], s[36:37], exec
	s_and_b64 s[34:35], s[34:35], exec
	s_and_b64 s[30:31], s[30:31], exec
	s_and_b64 s[28:29], s[28:29], exec
	s_and_b64 s[24:25], s[24:25], exec
	s_and_b64 s[22:23], s[22:23], exec
	s_and_b64 s[20:21], s[20:21], exec
	s_and_b64 s[18:19], s[18:19], exec
	s_and_b64 s[0:1], s[0:1], exec
	s_or_b64 s[84:85], s[82:83], exec
	s_or_b64 s[50:51], s[54:55], s[50:51]
	s_or_b64 s[48:49], s[54:55], s[48:49]
	s_or_b64 s[46:47], s[54:55], s[46:47]
	s_or_b64 s[44:45], s[54:55], s[44:45]
	s_or_b64 s[42:43], s[54:55], s[42:43]
	s_or_b64 s[40:41], s[54:55], s[40:41]
	s_or_b64 s[38:39], s[54:55], s[38:39]
	s_or_b64 s[36:37], s[54:55], s[36:37]
	s_or_b64 s[34:35], s[54:55], s[34:35]
	s_or_b64 s[30:31], s[54:55], s[30:31]
	s_or_b64 s[28:29], s[54:55], s[28:29]
	s_or_b64 s[24:25], s[54:55], s[24:25]
	s_or_b64 s[22:23], s[54:55], s[22:23]
	s_or_b64 s[20:21], s[54:55], s[20:21]
	s_or_b64 s[18:19], s[54:55], s[18:19]
	s_or_b64 s[0:1], s[54:55], s[0:1]

.LBB0_1641:
	v_fmac_f32_e32 v209, v176, v16
	v_cvt_pk_bf16_f32 v148, v0, v1
	v_cvt_pk_bf16_f32 v149, v2, v3
	v_cvt_pk_bf16_f32 v150, v4, v5
	v_cvt_pk_bf16_f32 v151, v6, v7
	s_nop 1
	ds_read_b128 v[4:7], v242 offset:18432
	s_waitcnt lgkmcnt(7)
	v_mfma_f32_16x16x32_bf16 v[104:107], v[226:229], v[148:151], v[104:107]
	s_waitcnt lgkmcnt(6)
	v_mfma_f32_16x16x32_bf16 v[100:103], v[230:233], v[148:151], v[100:103]
	s_waitcnt lgkmcnt(5)
	v_mfma_f32_16x16x32_bf16 v[96:99], v[234:237], v[148:151], v[96:99]
	s_waitcnt lgkmcnt(4)
	v_mfma_f32_16x16x32_bf16 v[92:95], v[210:213], v[148:151], v[92:95]
	s_waitcnt lgkmcnt(3)
	v_mfma_f32_16x16x32_bf16 v[88:91], v[214:217], v[148:151], v[88:91]
	s_waitcnt lgkmcnt(2)
	v_mfma_f32_16x16x32_bf16 v[84:87], v[222:225], v[148:151], v[84:87]
	s_waitcnt lgkmcnt(1)
	v_mfma_f32_16x16x32_bf16 v[0:3], v[238:241], v[148:151], v[112:115]
	s_waitcnt lgkmcnt(0)
	v_mfma_f32_16x16x32_bf16 v[4:7], v[4:7], v[148:151], v[108:111]
	v_add_u32_e32 v16, v202, v204
	v_cvt_pk_bf16_f32 v148, v8, v9
	v_cvt_pk_bf16_f32 v149, v10, v11
	v_cvt_pk_bf16_f32 v150, v12, v13
	v_cvt_pk_bf16_f32 v151, v14, v15
	s_nop 1
	ds_read_b128 v[8:11], v16 offset:16384
	ds_read_b128 v[12:15], v16 offset:18432
	ds_read_b128 v[152:155], v16 offset:20480
	ds_read_b128 v[156:159], v16 offset:22528
	ds_read_b128 v[160:163], v16 offset:24576
	ds_read_b128 v[210:213], v16 offset:26624
	ds_read_b128 v[214:217], v16 offset:28672
	ds_read_b128 v[222:225], v16 offset:30720
	s_waitcnt lgkmcnt(7)
	v_mfma_f32_16x16x32_bf16 v[112:115], v[8:11], v[148:151], v[0:3]
	s_waitcnt lgkmcnt(6)
	v_mfma_f32_16x16x32_bf16 v[108:111], v[12:15], v[148:151], v[4:7]
	s_waitcnt lgkmcnt(5)
	v_mfma_f32_16x16x32_bf16 v[104:107], v[152:155], v[148:151], v[104:107]
	s_waitcnt lgkmcnt(4)
	v_mfma_f32_16x16x32_bf16 v[100:103], v[156:159], v[148:151], v[100:103]
	s_waitcnt lgkmcnt(3)
	v_mfma_f32_16x16x32_bf16 v[96:99], v[160:163], v[148:151], v[96:99]
	s_waitcnt lgkmcnt(2)
	v_mfma_f32_16x16x32_bf16 v[92:95], v[210:213], v[148:151], v[92:95]
	s_waitcnt lgkmcnt(1)
	v_mfma_f32_16x16x32_bf16 v[88:91], v[214:217], v[148:151], v[88:91]
	s_waitcnt lgkmcnt(0)
	v_mfma_f32_16x16x32_bf16 v[84:87], v[222:225], v[148:151], v[84:87]
	v_mov_b32_e32 v176, v209
	v_mov_b32_e32 v18, v208
.LBB0_1642:
	s_or_b64 exec, exec, s[80:81]
	v_and_b32_e32 v0, 0xf0, v207
	v_cmp_ne_u32_e32 vcc, 0, v0
	s_and_saveexec_b64 s[80:81], vcc
	s_cbranch_execz .LBB0_1652
	v_lshrrev_b32_e32 v242, 4, v207
	v_and_b32_e32 v242, v242, v186
	v_cmp_ne_u32_e64 s[82:83], 0, v242
	ds_read_b128 v[0:3], v187
	ds_read_b128 v[4:7], v188
	ds_read_b128 v[8:11], v189
	ds_read_b128 v[12:15], v190
	ds_read_b128 v[148:151], v191
	ds_read_b128 v[152:155], v192
	ds_read_b128 v[156:159], v193
	ds_read_b128 v[208:211], v194
	ds_read_b128 v[226:229], v187 offset:8192
	ds_read_b128 v[230:233], v195
	ds_read_b128 v[234:237], v189 offset:8192
	ds_read_b128 v[238:241], v196
	ds_read_b128 v[212:215], v198
	s_waitcnt lgkmcnt(12)
	v_mfma_f32_16x16x32_bf16 v[0:3], v[0:3], v[36:39], 0
	s_waitcnt lgkmcnt(11)
	v_mfma_f32_16x16x32_bf16 v[4:7], v[4:7], v[36:39], 0
	s_waitcnt lgkmcnt(10)
	v_mfma_f32_16x16x32_bf16 v[0:3], v[8:11], v[40:43], v[0:3]
	s_waitcnt lgkmcnt(9)
	v_mfma_f32_16x16x32_bf16 v[4:7], v[12:15], v[40:43], v[4:7]
	s_waitcnt lgkmcnt(8)
	v_mfma_f32_16x16x32_bf16 v[0:3], v[148:151], v[44:47], v[0:3]
	ds_read_b128 v[148:151], v191 offset:8192
	s_waitcnt lgkmcnt(8)
	v_mfma_f32_16x16x32_bf16 v[4:7], v[152:155], v[44:47], v[4:7]
	ds_read_b128 v[152:155], v197
	s_waitcnt lgkmcnt(8)
	v_mfma_f32_16x16x32_bf16 v[160:163], v[156:159], v[48:51], v[0:3]
	s_waitcnt lgkmcnt(7)
	v_mfma_f32_16x16x32_bf16 v[156:159], v[208:211], v[48:51], v[4:7]
	ds_read_b128 v[208:211], v193 offset:8192
	s_waitcnt lgkmcnt(7)
	v_mfma_f32_16x16x32_bf16 v[0:3], v[226:229], v[36:39], 0
	s_waitcnt lgkmcnt(6)
	v_mfma_f32_16x16x32_bf16 v[4:7], v[230:233], v[36:39], 0
	s_waitcnt lgkmcnt(5)
	v_mfma_f32_16x16x32_bf16 v[0:3], v[234:237], v[40:43], v[0:3]
	s_waitcnt lgkmcnt(4)
	v_mfma_f32_16x16x32_bf16 v[4:7], v[238:241], v[40:43], v[4:7]
	s_waitcnt lgkmcnt(2)
	v_mfma_f32_16x16x32_bf16 v[0:3], v[148:151], v[44:47], v[0:3]
	s_waitcnt lgkmcnt(1)
	v_mfma_f32_16x16x32_bf16 v[4:7], v[152:155], v[44:47], v[4:7]
	s_waitcnt lgkmcnt(0)
	v_mfma_f32_16x16x32_bf16 v[152:155], v[208:211], v[48:51], v[0:3]
	v_mfma_f32_16x16x32_bf16 v[148:151], v[212:215], v[48:51], v[4:7]
	v_add_u32_e32 v242, v202, v203
	ds_read_b128 v[226:229], v242 offset:20480
	ds_read_b128 v[230:233], v242 offset:22528
	ds_read_b128 v[234:237], v242 offset:24576
	ds_read_b128 v[210:213], v242 offset:26624
	ds_read_b128 v[214:217], v242 offset:28672
	ds_read_b128 v[222:225], v242 offset:30720
	ds_read_b128 v[238:241], v242 offset:16384
	s_lshl_b32 s33, s94, 6
	s_or_b32 s0, s33, 59
	v_cmp_le_i32_e32 vcc, s0, v199
	s_and_saveexec_b64 s[0:1], vcc
	s_xor_b64 s[0:1], exec, s[0:1]
	s_or_saveexec_b64 s[26:27], s[0:1]
	s_mov_b64 s[84:85], s[82:83]
	s_xor_b64 exec, exec, s[26:27]
	s_cbranch_execz .LBB0_1645
	v_cndmask_b32_e64 v1, 0, -1, s[82:83]
	v_or_b32_e32 v2, s33, v201
	v_cndmask_b32_e64 v0, -1, v205, s[82:83]
	v_cmp_gt_i32_e64 s[0:1], v2, v1
	v_or_b32_e32 v1, 2, v2
	v_cmp_le_i32_e64 s[20:21], v1, v0
	v_or_b32_e32 v1, 3, v2
	v_cmp_le_i32_e64 s[22:23], v1, v0
	v_or_b32_e32 v1, 4, v2
	v_cmp_le_i32_e64 s[24:25], v1, v0
	v_or_b32_e32 v1, 5, v2
	v_cmp_le_i32_e64 s[28:29], v1, v0
	v_or_b32_e32 v1, 6, v2
	v_cmp_le_i32_e64 s[30:31], v1, v0
	v_or_b32_e32 v1, 7, v2
	v_cmp_le_i32_e64 s[34:35], v1, v0
	v_or_b32_e32 v1, 32, v2
	v_cmp_le_i32_e64 s[36:37], v1, v0
	v_cmp_lt_i32_e64 s[38:39], v1, v0
	v_or_b32_e32 v1, 34, v2
	v_cmp_le_i32_e64 s[40:41], v1, v0
	v_or_b32_e32 v1, 35, v2
	v_cmp_le_i32_e64 s[42:43], v1, v0
	v_or_b32_e32 v1, 36, v2
	v_cmp_le_i32_e64 s[44:45], v1, v0
	v_or_b32_e32 v1, 37, v2
	v_cmp_le_i32_e64 s[46:47], v1, v0
	v_or_b32_e32 v1, 38, v2
	v_cmp_le_i32_e64 s[18:19], v2, v0
	v_cmp_le_i32_e64 s[48:49], v1, v0
	v_or_b32_e32 v1, 39, v2
	s_and_b64 s[0:1], s[0:1], s[18:19]
	v_cmp_lt_i32_e64 s[18:19], v2, v0
	v_cmp_le_i32_e64 s[50:51], v1, v0
	v_cndmask_b32_e64 v160, v169, v160, s[0:1]
	v_cndmask_b32_e64 v161, v169, v161, s[18:19]
	v_cndmask_b32_e64 v162, v169, v162, s[20:21]
	v_cndmask_b32_e64 v163, v169, v163, s[22:23]
	v_cndmask_b32_e64 v156, v169, v156, s[24:25]
	v_cndmask_b32_e64 v157, v169, v157, s[28:29]
	v_cndmask_b32_e64 v158, v169, v158, s[30:31]
	v_cndmask_b32_e64 v159, v169, v159, s[34:35]
	v_cndmask_b32_e64 v152, v169, v152, s[36:37]
	v_cndmask_b32_e64 v153, v169, v153, s[38:39]
	v_cndmask_b32_e64 v154, v169, v154, s[40:41]
	v_cndmask_b32_e64 v155, v169, v155, s[42:43]
	v_cndmask_b32_e64 v148, v169, v148, s[44:45]
	v_cndmask_b32_e64 v149, v169, v149, s[46:47]
	v_cndmask_b32_e64 v150, v169, v150, s[48:49]
	v_cndmask_b32_e64 v151, v169, v151, s[50:51]
	s_andn2_b64 s[54:55], s[82:83], exec
	s_and_b64 s[50:51], s[50:51], exec
	s_and_b64 s[48:49], s[48:49], exec
	s_and_b64 s[46:47], s[46:47], exec
	s_and_b64 s[44:45], s[44:45], exec
	s_and_b64 s[42:43], s[42:43], exec
	s_and_b64 s[40:41], s[40:41], exec
	s_and_b64 s[38:39], s[38:39], exec
	s_and_b64 s[36:37], s[36:37], exec
	s_and_b64 s[34:35], s[34:35], exec
	s_and_b64 s[30:31], s[30:31], exec
	s_and_b64 s[28:29], s[28:29], exec
	s_and_b64 s[24:25], s[24:25], exec
	s_and_b64 s[22:23], s[22:23], exec
	s_and_b64 s[20:21], s[20:21], exec
	s_and_b64 s[18:19], s[18:19], exec
	s_and_b64 s[0:1], s[0:1], exec
	s_or_b64 s[84:85], s[82:83], exec
	s_or_b64 s[50:51], s[54:55], s[50:51]
	s_or_b64 s[48:49], s[54:55], s[48:49]
	s_or_b64 s[46:47], s[54:55], s[46:47]
	s_or_b64 s[44:45], s[54:55], s[44:45]
	s_or_b64 s[42:43], s[54:55], s[42:43]
	s_or_b64 s[40:41], s[54:55], s[40:41]
	s_or_b64 s[38:39], s[54:55], s[38:39]
	s_or_b64 s[36:37], s[54:55], s[36:37]
	s_or_b64 s[34:35], s[54:55], s[34:35]
	s_or_b64 s[30:31], s[54:55], s[30:31]
	s_or_b64 s[28:29], s[54:55], s[28:29]
	s_or_b64 s[24:25], s[54:55], s[24:25]
	s_or_b64 s[22:23], s[54:55], s[22:23]
	s_or_b64 s[20:21], s[54:55], s[20:21]
	s_or_b64 s[18:19], s[54:55], s[18:19]
	s_or_b64 s[0:1], s[54:55], s[0:1]

.LBB0_1651:
	v_fmac_f32_e32 v208, v175, v16
	v_cvt_pk_bf16_f32 v148, v0, v1
	v_cvt_pk_bf16_f32 v149, v2, v3
	v_cvt_pk_bf16_f32 v150, v4, v5
	v_cvt_pk_bf16_f32 v151, v6, v7
	s_nop 1
	ds_read_b128 v[4:7], v242 offset:18432
	s_waitcnt lgkmcnt(7)
	v_mfma_f32_16x16x32_bf16 v[72:75], v[226:229], v[148:151], v[72:75]
	s_waitcnt lgkmcnt(6)
	v_mfma_f32_16x16x32_bf16 v[68:71], v[230:233], v[148:151], v[68:71]
	s_waitcnt lgkmcnt(5)
	v_mfma_f32_16x16x32_bf16 v[64:67], v[234:237], v[148:151], v[64:67]
	s_waitcnt lgkmcnt(4)
	v_mfma_f32_16x16x32_bf16 v[60:63], v[210:213], v[148:151], v[60:63]
	s_waitcnt lgkmcnt(3)
	v_mfma_f32_16x16x32_bf16 v[56:59], v[214:217], v[148:151], v[56:59]
	s_waitcnt lgkmcnt(2)
	v_mfma_f32_16x16x32_bf16 v[52:55], v[222:225], v[148:151], v[52:55]
	s_waitcnt lgkmcnt(1)
	v_mfma_f32_16x16x32_bf16 v[0:3], v[238:241], v[148:151], v[80:83]
	s_waitcnt lgkmcnt(0)
	v_mfma_f32_16x16x32_bf16 v[4:7], v[4:7], v[148:151], v[76:79]
	v_add_u32_e32 v16, v202, v204
	v_cvt_pk_bf16_f32 v148, v8, v9
	v_cvt_pk_bf16_f32 v149, v10, v11
	v_cvt_pk_bf16_f32 v150, v12, v13
	v_cvt_pk_bf16_f32 v151, v14, v15
	s_nop 1
	ds_read_b128 v[8:11], v16 offset:16384
	ds_read_b128 v[12:15], v16 offset:18432
	ds_read_b128 v[152:155], v16 offset:20480
	ds_read_b128 v[156:159], v16 offset:22528
	ds_read_b128 v[160:163], v16 offset:24576
	ds_read_b128 v[210:213], v16 offset:26624
	ds_read_b128 v[214:217], v16 offset:28672
	ds_read_b128 v[222:225], v16 offset:30720
	s_waitcnt lgkmcnt(7)
	v_mfma_f32_16x16x32_bf16 v[80:83], v[8:11], v[148:151], v[0:3]
	s_waitcnt lgkmcnt(6)
	v_mfma_f32_16x16x32_bf16 v[76:79], v[12:15], v[148:151], v[4:7]
	s_waitcnt lgkmcnt(5)
	v_mfma_f32_16x16x32_bf16 v[72:75], v[152:155], v[148:151], v[72:75]
	s_waitcnt lgkmcnt(4)
	v_mfma_f32_16x16x32_bf16 v[68:71], v[156:159], v[148:151], v[68:71]
	s_waitcnt lgkmcnt(3)
	v_mfma_f32_16x16x32_bf16 v[64:67], v[160:163], v[148:151], v[64:67]
	s_waitcnt lgkmcnt(2)
	v_mfma_f32_16x16x32_bf16 v[60:63], v[210:213], v[148:151], v[60:63]
	s_waitcnt lgkmcnt(1)
	v_mfma_f32_16x16x32_bf16 v[56:59], v[214:217], v[148:151], v[56:59]
	s_waitcnt lgkmcnt(0)
	v_mfma_f32_16x16x32_bf16 v[52:55], v[222:225], v[148:151], v[52:55]
	v_mov_b32_e32 v175, v208
	v_mov_b32_e32 v206, v207

.Lselb_1632:
	s_waitcnt vmcnt(0) lgkmcnt(0)
	s_barrier
	s_min_u32 s0, s95, 0xff
	s_lshl_b32 s0, s0, 2
	s_add_i32 s18, s0, 0x10200
	s_cmp_gt_u32 s95, s86
	s_cselect_b64 s[78:79], -1, 0
	s_and_b64 s[0:1], s[78:79], exec
	s_cselect_b32 s0, s94, s95
	s_lshl_b32 s56, s0, 14
	v_readfirstlane_b32 s24, v122
	s_mov_b32 m0, s24
	v_lshl_add_u64 v[140:141], v[124:125], 0, s[56:57]
	global_load_lds_dwordx4 v[140:141], off
	s_add_u32 m0, m0, 0x1000
	v_lshl_add_u64 v[140:141], v[126:127], 0, s[56:57]
	global_load_lds_dwordx4 v[140:141], off
	s_add_u32 m0, m0, 0x1000
	v_lshl_add_u64 v[140:141], v[128:129], 0, s[56:57]
	global_load_lds_dwordx4 v[140:141], off
	s_add_u32 m0, m0, 0x1000
	v_lshl_add_u64 v[140:141], v[130:131], 0, s[56:57]
	global_load_lds_dwordx4 v[140:141], off
	s_add_u32 m0, m0, 0x1000
	v_lshl_add_u64 v[140:141], v[132:133], 0, s[56:57]
	global_load_lds_dwordx4 v[140:141], off
	s_add_u32 m0, m0, 0x1000
	v_lshl_add_u64 v[140:141], v[134:135], 0, s[56:57]
	global_load_lds_dwordx4 v[140:141], off
	s_add_u32 m0, m0, 0x1000
	v_lshl_add_u64 v[140:141], v[136:137], 0, s[56:57]
	global_load_lds_dwordx4 v[140:141], off
	s_add_u32 m0, m0, 0x1000
	v_lshl_add_u64 v[140:141], v[138:139], 0, s[56:57]
	global_load_lds_dwordx4 v[140:141], off
	v_mov_b32_e32 v0, s18
	ds_read_b32 v19, v0
	v_readfirstlane_b32 s0, v2
	s_nop 1
	v_ashrrev_i32_e64 v207, v185, s0
	v_and_b32_e32 v0, 15, v207
	v_cmp_ne_u32_e32 vcc, 0, v0
	s_and_saveexec_b64 s[80:81], vcc
	s_cbranch_execz .Lselb_1642
	v_and_b32_e32 v242, v207, v186
	v_cmp_ne_u32_e64 s[82:83], 0, v242
	ds_read_b128 v[0:3], v187 offset:32768
	ds_read_b128 v[4:7], v188 offset:32768
	ds_read_b128 v[8:11], v189 offset:32768
	ds_read_b128 v[12:15], v190 offset:32768
	ds_read_b128 v[148:151], v191 offset:32768
	ds_read_b128 v[152:155], v192 offset:32768
	ds_read_b128 v[156:159], v193 offset:32768
	ds_read_b128 v[208:211], v194 offset:32768
	ds_read_b128 v[226:229], v187 offset:40960
	ds_read_b128 v[230:233], v195 offset:32768
	ds_read_b128 v[234:237], v189 offset:40960
	ds_read_b128 v[238:241], v196 offset:32768
	ds_read_b128 v[212:215], v198 offset:32768
	s_waitcnt lgkmcnt(12)
	v_mfma_f32_16x16x32_bf16 v[0:3], v[0:3], v[20:23], 0
	s_waitcnt lgkmcnt(11)
	v_mfma_f32_16x16x32_bf16 v[4:7], v[4:7], v[20:23], 0
	s_waitcnt lgkmcnt(10)
	v_mfma_f32_16x16x32_bf16 v[0:3], v[8:11], v[24:27], v[0:3]
	s_waitcnt lgkmcnt(9)
	v_mfma_f32_16x16x32_bf16 v[4:7], v[12:15], v[24:27], v[4:7]
	s_waitcnt lgkmcnt(8)
	v_mfma_f32_16x16x32_bf16 v[0:3], v[148:151], v[28:31], v[0:3]
	ds_read_b128 v[148:151], v191 offset:40960
	s_waitcnt lgkmcnt(8)
	v_mfma_f32_16x16x32_bf16 v[4:7], v[152:155], v[28:31], v[4:7]
	ds_read_b128 v[152:155], v197 offset:32768
	s_waitcnt lgkmcnt(8)
	v_mfma_f32_16x16x32_bf16 v[160:163], v[156:159], v[32:35], v[0:3]
	s_waitcnt lgkmcnt(7)
	v_mfma_f32_16x16x32_bf16 v[156:159], v[208:211], v[32:35], v[4:7]
	ds_read_b128 v[208:211], v193 offset:40960
	s_waitcnt lgkmcnt(7)
	v_mfma_f32_16x16x32_bf16 v[0:3], v[226:229], v[20:23], 0
	s_waitcnt lgkmcnt(6)
	v_mfma_f32_16x16x32_bf16 v[4:7], v[230:233], v[20:23], 0
	s_waitcnt lgkmcnt(5)
	v_mfma_f32_16x16x32_bf16 v[0:3], v[234:237], v[24:27], v[0:3]
	s_waitcnt lgkmcnt(4)
	v_mfma_f32_16x16x32_bf16 v[4:7], v[238:241], v[24:27], v[4:7]
	s_waitcnt lgkmcnt(2)
	v_mfma_f32_16x16x32_bf16 v[0:3], v[148:151], v[28:31], v[0:3]
	s_waitcnt lgkmcnt(1)
	v_mfma_f32_16x16x32_bf16 v[4:7], v[152:155], v[28:31], v[4:7]
	s_waitcnt lgkmcnt(0)
	v_mfma_f32_16x16x32_bf16 v[152:155], v[208:211], v[32:35], v[0:3]
	v_mfma_f32_16x16x32_bf16 v[148:151], v[212:215], v[32:35], v[4:7]
	v_add_u32_e32 v242, v202, v203
	ds_read_b128 v[226:229], v242 offset:53248
	ds_read_b128 v[230:233], v242 offset:55296
	ds_read_b128 v[234:237], v242 offset:57344
	ds_read_b128 v[210:213], v242 offset:59392
	ds_read_b128 v[214:217], v242 offset:61440
	ds_read_b128 v[222:225], v242 offset:63488
	ds_read_b128 v[238:241], v242 offset:49152
	s_lshl_b32 s33, s94, 6
	s_or_b32 s0, s33, 63
	v_cmp_le_i32_e32 vcc, s0, v199
	s_and_saveexec_b64 s[0:1], vcc
	s_xor_b64 s[0:1], exec, s[0:1]
	s_or_saveexec_b64 s[26:27], s[0:1]
	s_mov_b64 s[84:85], s[82:83]
	s_xor_b64 exec, exec, s[26:27]
	s_cbranch_execz .Lselb_1635
	v_cndmask_b32_e64 v1, 0, -1, s[82:83]
	v_or_b32_e32 v2, s33, v201
	v_cndmask_b32_e64 v0, -1, v200, s[82:83]
	v_cmp_gt_i32_e64 s[0:1], v2, v1
	v_or_b32_e32 v1, 2, v2
	v_cmp_le_i32_e64 s[20:21], v1, v0
	v_or_b32_e32 v1, 3, v2
	v_cmp_le_i32_e64 s[22:23], v1, v0
	v_or_b32_e32 v1, 4, v2
	v_cmp_le_i32_e64 s[24:25], v1, v0
	v_or_b32_e32 v1, 5, v2
	v_cmp_le_i32_e64 s[28:29], v1, v0
	v_or_b32_e32 v1, 6, v2
	v_cmp_le_i32_e64 s[30:31], v1, v0
	v_or_b32_e32 v1, 7, v2
	v_cmp_le_i32_e64 s[34:35], v1, v0
	v_or_b32_e32 v1, 32, v2
	v_cmp_le_i32_e64 s[36:37], v1, v0
	v_cmp_lt_i32_e64 s[38:39], v1, v0
	v_or_b32_e32 v1, 34, v2
	v_cmp_le_i32_e64 s[40:41], v1, v0
	v_or_b32_e32 v1, 35, v2
	v_cmp_le_i32_e64 s[42:43], v1, v0
	v_or_b32_e32 v1, 36, v2
	v_cmp_le_i32_e64 s[44:45], v1, v0
	v_or_b32_e32 v1, 37, v2
	v_cmp_le_i32_e64 s[46:47], v1, v0
	v_or_b32_e32 v1, 38, v2
	v_cmp_le_i32_e64 s[18:19], v2, v0
	v_cmp_le_i32_e64 s[48:49], v1, v0
	v_or_b32_e32 v1, 39, v2
	s_and_b64 s[0:1], s[0:1], s[18:19]
	v_cmp_lt_i32_e64 s[18:19], v2, v0
	v_cmp_le_i32_e64 s[50:51], v1, v0
	v_cndmask_b32_e64 v160, v169, v160, s[0:1]
	v_cndmask_b32_e64 v161, v169, v161, s[18:19]
	v_cndmask_b32_e64 v162, v169, v162, s[20:21]
	v_cndmask_b32_e64 v163, v169, v163, s[22:23]
	v_cndmask_b32_e64 v156, v169, v156, s[24:25]
	v_cndmask_b32_e64 v157, v169, v157, s[28:29]
	v_cndmask_b32_e64 v158, v169, v158, s[30:31]
	v_cndmask_b32_e64 v159, v169, v159, s[34:35]
	v_cndmask_b32_e64 v152, v169, v152, s[36:37]
	v_cndmask_b32_e64 v153, v169, v153, s[38:39]
	v_cndmask_b32_e64 v154, v169, v154, s[40:41]
	v_cndmask_b32_e64 v155, v169, v155, s[42:43]
	v_cndmask_b32_e64 v148, v169, v148, s[44:45]
	v_cndmask_b32_e64 v149, v169, v149, s[46:47]
	v_cndmask_b32_e64 v150, v169, v150, s[48:49]
	v_cndmask_b32_e64 v151, v169, v151, s[50:51]
	s_andn2_b64 s[54:55], s[82:83], exec
	s_and_b64 s[50:51], s[50:51], exec
	s_and_b64 s[48:49], s[48:49], exec
	s_and_b64 s[46:47], s[46:47], exec
	s_and_b64 s[44:45], s[44:45], exec
	s_and_b64 s[42:43], s[42:43], exec
	s_and_b64 s[40:41], s[40:41], exec
	s_and_b64 s[38:39], s[38:39], exec
	s_and_b64 s[36:37], s[36:37], exec
	s_and_b64 s[34:35], s[34:35], exec
	s_and_b64 s[30:31], s[30:31], exec
	s_and_b64 s[28:29], s[28:29], exec
	s_and_b64 s[24:25], s[24:25], exec
	s_and_b64 s[22:23], s[22:23], exec
	s_and_b64 s[20:21], s[20:21], exec
	s_and_b64 s[18:19], s[18:19], exec
	s_and_b64 s[0:1], s[0:1], exec
	s_or_b64 s[84:85], s[82:83], exec
	s_or_b64 s[50:51], s[54:55], s[50:51]
	s_or_b64 s[48:49], s[54:55], s[48:49]
	s_or_b64 s[46:47], s[54:55], s[46:47]
	s_or_b64 s[44:45], s[54:55], s[44:45]
	s_or_b64 s[42:43], s[54:55], s[42:43]
	s_or_b64 s[40:41], s[54:55], s[40:41]
	s_or_b64 s[38:39], s[54:55], s[38:39]
	s_or_b64 s[36:37], s[54:55], s[36:37]
	s_or_b64 s[34:35], s[54:55], s[34:35]
	s_or_b64 s[30:31], s[54:55], s[30:31]
	s_or_b64 s[28:29], s[54:55], s[28:29]
	s_or_b64 s[24:25], s[54:55], s[24:25]
	s_or_b64 s[22:23], s[54:55], s[22:23]
	s_or_b64 s[20:21], s[54:55], s[20:21]
	s_or_b64 s[18:19], s[54:55], s[18:19]
	s_or_b64 s[0:1], s[54:55], s[0:1]

.Lselb_1641:
	v_fmac_f32_e32 v209, v176, v16
	v_cvt_pk_bf16_f32 v148, v0, v1
	v_cvt_pk_bf16_f32 v149, v2, v3
	v_cvt_pk_bf16_f32 v150, v4, v5
	v_cvt_pk_bf16_f32 v151, v6, v7
	s_nop 1
	ds_read_b128 v[4:7], v242 offset:51200
	s_waitcnt lgkmcnt(7)
	v_mfma_f32_16x16x32_bf16 v[104:107], v[226:229], v[148:151], v[104:107]
	s_waitcnt lgkmcnt(6)
	v_mfma_f32_16x16x32_bf16 v[100:103], v[230:233], v[148:151], v[100:103]
	s_waitcnt lgkmcnt(5)
	v_mfma_f32_16x16x32_bf16 v[96:99], v[234:237], v[148:151], v[96:99]
	s_waitcnt lgkmcnt(4)
	v_mfma_f32_16x16x32_bf16 v[92:95], v[210:213], v[148:151], v[92:95]
	s_waitcnt lgkmcnt(3)
	v_mfma_f32_16x16x32_bf16 v[88:91], v[214:217], v[148:151], v[88:91]
	s_waitcnt lgkmcnt(2)
	v_mfma_f32_16x16x32_bf16 v[84:87], v[222:225], v[148:151], v[84:87]
	s_waitcnt lgkmcnt(1)
	v_mfma_f32_16x16x32_bf16 v[0:3], v[238:241], v[148:151], v[112:115]
	s_waitcnt lgkmcnt(0)
	v_mfma_f32_16x16x32_bf16 v[4:7], v[4:7], v[148:151], v[108:111]
	v_add_u32_e32 v16, v202, v204
	v_cvt_pk_bf16_f32 v148, v8, v9
	v_cvt_pk_bf16_f32 v149, v10, v11
	v_cvt_pk_bf16_f32 v150, v12, v13
	v_cvt_pk_bf16_f32 v151, v14, v15
	s_nop 1
	ds_read_b128 v[8:11], v16 offset:49152
	ds_read_b128 v[12:15], v16 offset:51200
	ds_read_b128 v[152:155], v16 offset:53248
	ds_read_b128 v[156:159], v16 offset:55296
	ds_read_b128 v[160:163], v16 offset:57344
	ds_read_b128 v[210:213], v16 offset:59392
	ds_read_b128 v[214:217], v16 offset:61440
	ds_read_b128 v[222:225], v16 offset:63488
	s_waitcnt lgkmcnt(7)
	v_mfma_f32_16x16x32_bf16 v[112:115], v[8:11], v[148:151], v[0:3]
	s_waitcnt lgkmcnt(6)
	v_mfma_f32_16x16x32_bf16 v[108:111], v[12:15], v[148:151], v[4:7]
	s_waitcnt lgkmcnt(5)
	v_mfma_f32_16x16x32_bf16 v[104:107], v[152:155], v[148:151], v[104:107]
	s_waitcnt lgkmcnt(4)
	v_mfma_f32_16x16x32_bf16 v[100:103], v[156:159], v[148:151], v[100:103]
	s_waitcnt lgkmcnt(3)
	v_mfma_f32_16x16x32_bf16 v[96:99], v[160:163], v[148:151], v[96:99]
	s_waitcnt lgkmcnt(2)
	v_mfma_f32_16x16x32_bf16 v[92:95], v[210:213], v[148:151], v[92:95]
	s_waitcnt lgkmcnt(1)
	v_mfma_f32_16x16x32_bf16 v[88:91], v[214:217], v[148:151], v[88:91]
	s_waitcnt lgkmcnt(0)
	v_mfma_f32_16x16x32_bf16 v[84:87], v[222:225], v[148:151], v[84:87]
	v_mov_b32_e32 v176, v209
	v_mov_b32_e32 v18, v208
.Lselb_1642:
	s_or_b64 exec, exec, s[80:81]
	v_and_b32_e32 v0, 0xf0, v207
	v_cmp_ne_u32_e32 vcc, 0, v0
	s_and_saveexec_b64 s[80:81], vcc
	s_cbranch_execz .Lselb_1652
	v_lshrrev_b32_e32 v242, 4, v207
	v_and_b32_e32 v242, v242, v186
	v_cmp_ne_u32_e64 s[82:83], 0, v242
	ds_read_b128 v[0:3], v187 offset:32768
	ds_read_b128 v[4:7], v188 offset:32768
	ds_read_b128 v[8:11], v189 offset:32768
	ds_read_b128 v[12:15], v190 offset:32768
	ds_read_b128 v[148:151], v191 offset:32768
	ds_read_b128 v[152:155], v192 offset:32768
	ds_read_b128 v[156:159], v193 offset:32768
	ds_read_b128 v[208:211], v194 offset:32768
	ds_read_b128 v[226:229], v187 offset:40960
	ds_read_b128 v[230:233], v195 offset:32768
	ds_read_b128 v[234:237], v189 offset:40960
	ds_read_b128 v[238:241], v196 offset:32768
	ds_read_b128 v[212:215], v198 offset:32768
	s_waitcnt lgkmcnt(12)
	v_mfma_f32_16x16x32_bf16 v[0:3], v[0:3], v[36:39], 0
	s_waitcnt lgkmcnt(11)
	v_mfma_f32_16x16x32_bf16 v[4:7], v[4:7], v[36:39], 0
	s_waitcnt lgkmcnt(10)
	v_mfma_f32_16x16x32_bf16 v[0:3], v[8:11], v[40:43], v[0:3]
	s_waitcnt lgkmcnt(9)
	v_mfma_f32_16x16x32_bf16 v[4:7], v[12:15], v[40:43], v[4:7]
	s_waitcnt lgkmcnt(8)
	v_mfma_f32_16x16x32_bf16 v[0:3], v[148:151], v[44:47], v[0:3]
	ds_read_b128 v[148:151], v191 offset:40960
	s_waitcnt lgkmcnt(8)
	v_mfma_f32_16x16x32_bf16 v[4:7], v[152:155], v[44:47], v[4:7]
	ds_read_b128 v[152:155], v197 offset:32768
	s_waitcnt lgkmcnt(8)
	v_mfma_f32_16x16x32_bf16 v[160:163], v[156:159], v[48:51], v[0:3]
	s_waitcnt lgkmcnt(7)
	v_mfma_f32_16x16x32_bf16 v[156:159], v[208:211], v[48:51], v[4:7]
	ds_read_b128 v[208:211], v193 offset:40960
	s_waitcnt lgkmcnt(7)
	v_mfma_f32_16x16x32_bf16 v[0:3], v[226:229], v[36:39], 0
	s_waitcnt lgkmcnt(6)
	v_mfma_f32_16x16x32_bf16 v[4:7], v[230:233], v[36:39], 0
	s_waitcnt lgkmcnt(5)
	v_mfma_f32_16x16x32_bf16 v[0:3], v[234:237], v[40:43], v[0:3]
	s_waitcnt lgkmcnt(4)
	v_mfma_f32_16x16x32_bf16 v[4:7], v[238:241], v[40:43], v[4:7]
	s_waitcnt lgkmcnt(2)
	v_mfma_f32_16x16x32_bf16 v[0:3], v[148:151], v[44:47], v[0:3]
	s_waitcnt lgkmcnt(1)
	v_mfma_f32_16x16x32_bf16 v[4:7], v[152:155], v[44:47], v[4:7]
	s_waitcnt lgkmcnt(0)
	v_mfma_f32_16x16x32_bf16 v[152:155], v[208:211], v[48:51], v[0:3]
	v_mfma_f32_16x16x32_bf16 v[148:151], v[212:215], v[48:51], v[4:7]
	v_add_u32_e32 v242, v202, v203
	ds_read_b128 v[226:229], v242 offset:53248
	ds_read_b128 v[230:233], v242 offset:55296
	ds_read_b128 v[234:237], v242 offset:57344
	ds_read_b128 v[210:213], v242 offset:59392
	ds_read_b128 v[214:217], v242 offset:61440
	ds_read_b128 v[222:225], v242 offset:63488
	ds_read_b128 v[238:241], v242 offset:49152
	s_lshl_b32 s33, s94, 6
	s_or_b32 s0, s33, 59
	v_cmp_le_i32_e32 vcc, s0, v199
	s_and_saveexec_b64 s[0:1], vcc
	s_xor_b64 s[0:1], exec, s[0:1]
	s_or_saveexec_b64 s[26:27], s[0:1]
	s_mov_b64 s[84:85], s[82:83]
	s_xor_b64 exec, exec, s[26:27]
	s_cbranch_execz .Lselb_1645
	v_cndmask_b32_e64 v1, 0, -1, s[82:83]
	v_or_b32_e32 v2, s33, v201
	v_cndmask_b32_e64 v0, -1, v205, s[82:83]
	v_cmp_gt_i32_e64 s[0:1], v2, v1
	v_or_b32_e32 v1, 2, v2
	v_cmp_le_i32_e64 s[20:21], v1, v0
	v_or_b32_e32 v1, 3, v2
	v_cmp_le_i32_e64 s[22:23], v1, v0
	v_or_b32_e32 v1, 4, v2
	v_cmp_le_i32_e64 s[24:25], v1, v0
	v_or_b32_e32 v1, 5, v2
	v_cmp_le_i32_e64 s[28:29], v1, v0
	v_or_b32_e32 v1, 6, v2
	v_cmp_le_i32_e64 s[30:31], v1, v0
	v_or_b32_e32 v1, 7, v2
	v_cmp_le_i32_e64 s[34:35], v1, v0
	v_or_b32_e32 v1, 32, v2
	v_cmp_le_i32_e64 s[36:37], v1, v0
	v_cmp_lt_i32_e64 s[38:39], v1, v0
	v_or_b32_e32 v1, 34, v2
	v_cmp_le_i32_e64 s[40:41], v1, v0
	v_or_b32_e32 v1, 35, v2
	v_cmp_le_i32_e64 s[42:43], v1, v0
	v_or_b32_e32 v1, 36, v2
	v_cmp_le_i32_e64 s[44:45], v1, v0
	v_or_b32_e32 v1, 37, v2
	v_cmp_le_i32_e64 s[46:47], v1, v0
	v_or_b32_e32 v1, 38, v2
	v_cmp_le_i32_e64 s[18:19], v2, v0
	v_cmp_le_i32_e64 s[48:49], v1, v0
	v_or_b32_e32 v1, 39, v2
	s_and_b64 s[0:1], s[0:1], s[18:19]
	v_cmp_lt_i32_e64 s[18:19], v2, v0
	v_cmp_le_i32_e64 s[50:51], v1, v0
	v_cndmask_b32_e64 v160, v169, v160, s[0:1]
	v_cndmask_b32_e64 v161, v169, v161, s[18:19]
	v_cndmask_b32_e64 v162, v169, v162, s[20:21]
	v_cndmask_b32_e64 v163, v169, v163, s[22:23]
	v_cndmask_b32_e64 v156, v169, v156, s[24:25]
	v_cndmask_b32_e64 v157, v169, v157, s[28:29]
	v_cndmask_b32_e64 v158, v169, v158, s[30:31]
	v_cndmask_b32_e64 v159, v169, v159, s[34:35]
	v_cndmask_b32_e64 v152, v169, v152, s[36:37]
	v_cndmask_b32_e64 v153, v169, v153, s[38:39]
	v_cndmask_b32_e64 v154, v169, v154, s[40:41]
	v_cndmask_b32_e64 v155, v169, v155, s[42:43]
	v_cndmask_b32_e64 v148, v169, v148, s[44:45]
	v_cndmask_b32_e64 v149, v169, v149, s[46:47]
	v_cndmask_b32_e64 v150, v169, v150, s[48:49]
	v_cndmask_b32_e64 v151, v169, v151, s[50:51]
	s_andn2_b64 s[54:55], s[82:83], exec
	s_and_b64 s[50:51], s[50:51], exec
	s_and_b64 s[48:49], s[48:49], exec
	s_and_b64 s[46:47], s[46:47], exec
	s_and_b64 s[44:45], s[44:45], exec
	s_and_b64 s[42:43], s[42:43], exec
	s_and_b64 s[40:41], s[40:41], exec
	s_and_b64 s[38:39], s[38:39], exec
	s_and_b64 s[36:37], s[36:37], exec
	s_and_b64 s[34:35], s[34:35], exec
	s_and_b64 s[30:31], s[30:31], exec
	s_and_b64 s[28:29], s[28:29], exec
	s_and_b64 s[24:25], s[24:25], exec
	s_and_b64 s[22:23], s[22:23], exec
	s_and_b64 s[20:21], s[20:21], exec
	s_and_b64 s[18:19], s[18:19], exec
	s_and_b64 s[0:1], s[0:1], exec
	s_or_b64 s[84:85], s[82:83], exec
	s_or_b64 s[50:51], s[54:55], s[50:51]
	s_or_b64 s[48:49], s[54:55], s[48:49]
	s_or_b64 s[46:47], s[54:55], s[46:47]
	s_or_b64 s[44:45], s[54:55], s[44:45]
	s_or_b64 s[42:43], s[54:55], s[42:43]
	s_or_b64 s[40:41], s[54:55], s[40:41]
	s_or_b64 s[38:39], s[54:55], s[38:39]
	s_or_b64 s[36:37], s[54:55], s[36:37]
	s_or_b64 s[34:35], s[54:55], s[34:35]
	s_or_b64 s[30:31], s[54:55], s[30:31]
	s_or_b64 s[28:29], s[54:55], s[28:29]
	s_or_b64 s[24:25], s[54:55], s[24:25]
	s_or_b64 s[22:23], s[54:55], s[22:23]
	s_or_b64 s[20:21], s[54:55], s[20:21]
	s_or_b64 s[18:19], s[54:55], s[18:19]
	s_or_b64 s[0:1], s[54:55], s[0:1]

.Lselb_1651:
	v_fmac_f32_e32 v208, v175, v16
	v_cvt_pk_bf16_f32 v148, v0, v1
	v_cvt_pk_bf16_f32 v149, v2, v3
	v_cvt_pk_bf16_f32 v150, v4, v5
	v_cvt_pk_bf16_f32 v151, v6, v7
	s_nop 1
	ds_read_b128 v[4:7], v242 offset:51200
	s_waitcnt lgkmcnt(7)
	v_mfma_f32_16x16x32_bf16 v[72:75], v[226:229], v[148:151], v[72:75]
	s_waitcnt lgkmcnt(6)
	v_mfma_f32_16x16x32_bf16 v[68:71], v[230:233], v[148:151], v[68:71]
	s_waitcnt lgkmcnt(5)
	v_mfma_f32_16x16x32_bf16 v[64:67], v[234:237], v[148:151], v[64:67]
	s_waitcnt lgkmcnt(4)
	v_mfma_f32_16x16x32_bf16 v[60:63], v[210:213], v[148:151], v[60:63]
	s_waitcnt lgkmcnt(3)
	v_mfma_f32_16x16x32_bf16 v[56:59], v[214:217], v[148:151], v[56:59]
	s_waitcnt lgkmcnt(2)
	v_mfma_f32_16x16x32_bf16 v[52:55], v[222:225], v[148:151], v[52:55]
	s_waitcnt lgkmcnt(1)
	v_mfma_f32_16x16x32_bf16 v[0:3], v[238:241], v[148:151], v[80:83]
	s_waitcnt lgkmcnt(0)
	v_mfma_f32_16x16x32_bf16 v[4:7], v[4:7], v[148:151], v[76:79]
	v_add_u32_e32 v16, v202, v204
	v_cvt_pk_bf16_f32 v148, v8, v9
	v_cvt_pk_bf16_f32 v149, v10, v11
	v_cvt_pk_bf16_f32 v150, v12, v13
	v_cvt_pk_bf16_f32 v151, v14, v15
	s_nop 1
	ds_read_b128 v[8:11], v16 offset:49152
	ds_read_b128 v[12:15], v16 offset:51200
	ds_read_b128 v[152:155], v16 offset:53248
	ds_read_b128 v[156:159], v16 offset:55296
	ds_read_b128 v[160:163], v16 offset:57344
	ds_read_b128 v[210:213], v16 offset:59392
	ds_read_b128 v[214:217], v16 offset:61440
	ds_read_b128 v[222:225], v16 offset:63488
	s_waitcnt lgkmcnt(7)
	v_mfma_f32_16x16x32_bf16 v[80:83], v[8:11], v[148:151], v[0:3]
	s_waitcnt lgkmcnt(6)
	v_mfma_f32_16x16x32_bf16 v[76:79], v[12:15], v[148:151], v[4:7]
	s_waitcnt lgkmcnt(5)
	v_mfma_f32_16x16x32_bf16 v[72:75], v[152:155], v[148:151], v[72:75]
	s_waitcnt lgkmcnt(4)
	v_mfma_f32_16x16x32_bf16 v[68:71], v[156:159], v[148:151], v[68:71]
	s_waitcnt lgkmcnt(3)
	v_mfma_f32_16x16x32_bf16 v[64:67], v[160:163], v[148:151], v[64:67]
	s_waitcnt lgkmcnt(2)
	v_mfma_f32_16x16x32_bf16 v[60:63], v[210:213], v[148:151], v[60:63]
	s_waitcnt lgkmcnt(1)
	v_mfma_f32_16x16x32_bf16 v[56:59], v[214:217], v[148:151], v[56:59]
	s_waitcnt lgkmcnt(0)
	v_mfma_f32_16x16x32_bf16 v[52:55], v[222:225], v[148:151], v[52:55]
	v_mov_b32_e32 v175, v208
	v_mov_b32_e32 v206, v207
